# diff loop: one seed tuple per iteration shared by both sub-tiles (rebuild skipped in the same far class), plus MLA persistent seed tuple
# speedup vs baseline: 1.0085x; 1.0085x over previous
; DI f32x16 mfma32(bf16x8 a, bf16x8 b, f32x16 c) { return __builtin_amdgcn_mfma_f32_32x32x16_bf16(a, b, c, 0, 0, 0); }
; DI void attn_diff_unit(const Params& p, int li, int b, int h, int qb, char* smem, bool pre, int nh, bool has_next) {
;     ...
;     for (int sub = 0; sub < 2; ++sub) {
;       const int kbase = kt * 128 + sub * 64;
;       const int relmin = kbase - (qb * 128 + 127), relmax = kbase + 63 - qb * 128;
;       const float cb = (relmin >= 128) ? cR : ((relmax <= -128) ? cL : 0.f);
;       f32x16 s0, s1;
; #pragma unroll
;       for (int i = 0; i < 16; ++i) { s0[i] = cb - m; s1[i] = cb - m; }
;       {
;         bf16x8 kf[8];
; #pragma unroll
;         for (int s = 0; s < 4; ++s) {
;           kf[2 * s] = *(const bf16x8*)(ks + (sub * 64 + r32) * KR + (map * 64 + s * 16 + hh * 8) * 2);
;           kf[2 * s + 1] = *(const bf16x8*)(ks + (sub * 64 + 32 + r32) * KR + (map * 64 + s * 16 + hh * 8) * 2);
;         }
;         __builtin_amdgcn_sched_barrier(0); __builtin_amdgcn_s_setprio(1);
; #pragma unroll
;         for (int s = 0; s < 4; ++s) { s0 = mfma32(kf[2 * s], qf[s], s0); s1 = mfma32(kf[2 * s + 1], qf[s], s1); }
;       __builtin_amdgcn_s_setprio(0);
; }
;       if (relmin < 128 && relmax > -128) {
;         const int base = kbase - qpos + 255 + 4 * hh;
; #pragma unroll
;         for (int i = 0; i < 16; ++i) {
;           int i0 = base + (i & 3) + 8 * (i >> 2);
;           int i1 = i0 + 32;
;           i0 = i0 < 0 ? 0 : (i0 > 510 ? 510 : i0);
;           i1 = i1 < 0 ? 0 : (i1 > 510 ? 510 : i1);
;           s0[i] += tab[i0]; s1[i] += tab[i1];
;         }
;       }
.LBB0_568:
	v_add_u32_e32 v76, s45, v167
	v_add_u32_e32 v174, v76, v165
	ds_read_b128 v[176:179], v174
	ds_read_b128 v[224:227], v174 offset:32
	ds_read_b128 v[228:231], v174 offset:8704
	ds_read_b128 v[232:235], v174 offset:8736
	ds_read_b128 v[242:245], v174 offset:64
	ds_read_b128 v[212:215], v174 offset:96
	ds_read_b128 v[216:219], v174 offset:8768
	ds_read_b128 v[220:223], v174 offset:8800
	s_add_i32 s44, s42, s24
	s_cmp_ge_i32 s44, 0xff
	s_cselect_b64 vcc, -1, 0
	s_cmp_le_i32 s44, 0xffffff41
	s_cselect_b64 s[2:3], -1, 0
	v_cndmask_b32_e64 v196, 0, v156, s[2:3]
	v_cndmask_b32_e32 v196, v196, v157, vcc
	v_sub_f32_e32 v196, v196, v169
	v_mov_b32_e32 v197, v196
	v_mov_b64_e32 v[198:199], v[196:197]
	v_mov_b64_e32 v[200:201], v[196:197]
	v_mov_b64_e32 v[202:203], v[196:197]
	v_mov_b64_e32 v[204:205], v[196:197]
	v_mov_b64_e32 v[206:207], v[196:197]
	v_mov_b64_e32 v[208:209], v[196:197]
	v_mov_b64_e32 v[210:211], v[196:197]
	s_nop 0
	s_waitcnt lgkmcnt(4)
	v_mfma_f32_32x32x16_bf16 v[80:95], v[176:179], v[96:99], v[196:211]
	v_mfma_f32_32x32x16_bf16 v[64:79], v[228:231], v[96:99], v[196:211]
	v_mfma_f32_32x32x16_bf16 v[80:95], v[224:227], v[100:103], v[80:95]
	v_mfma_f32_32x32x16_bf16 v[64:79], v[232:235], v[100:103], v[64:79]
	s_waitcnt lgkmcnt(0)
	v_mfma_f32_32x32x16_bf16 v[80:95], v[242:245], v[104:107], v[80:95]
	v_mfma_f32_32x32x16_bf16 v[64:79], v[216:219], v[104:107], v[64:79]
	v_mfma_f32_32x32x16_bf16 v[80:95], v[212:215], v[108:111], v[80:95]
	v_mfma_f32_32x32x16_bf16 v[64:79], v[220:223], v[108:111], v[64:79]
	s_or_b64 s[2:3], s[2:3], vcc
	v_add_u32_e32 v173, s24, v168
	s_and_b64 vcc, exec, s[2:3]
	s_cbranch_vccnz .LBB0_570
	v_add_u32_e32 v177, 0x100, v173
	s_add_i32 s2, 0, 0x25000
	v_med3_i32 v178, v177, 0, v192
	v_med3_i32 v177, v177, s33, v193
	v_lshl_add_u32 v180, v177, 2, s2
	v_add_u32_e32 v177, 0x101, v173
	v_lshl_add_u32 v179, v178, 2, s2
	v_med3_i32 v178, v177, 0, v192
	v_med3_i32 v177, v177, s33, v193
	v_add_u32_e32 v199, 0x108, v173
	v_add_u32_e32 v175, 0xff, v173
	v_lshl_add_u32 v196, v177, 2, s2
	v_add_u32_e32 v177, 0x102, v173
	v_med3_i32 v200, v199, 0, v192
	v_med3_i32 v199, v199, s33, v193
	v_med3_i32 v176, v175, 0, v192
	v_med3_i32 v175, v175, s33, v193
	v_lshl_add_u32 v181, v178, 2, s2
	v_med3_i32 v178, v177, 0, v192
	v_lshl_add_u32 v202, v199, 2, s2
	v_add_u32_e32 v199, 0x109, v173
	v_lshl_add_u32 v176, v176, 2, s2
	v_lshl_add_u32 v175, v175, 2, s2
	v_med3_i32 v177, v177, s33, v193
	v_lshl_add_u32 v197, v178, 2, s2
	v_lshl_add_u32 v201, v200, 2, s2
	v_med3_i32 v200, v199, 0, v192
	v_med3_i32 v199, v199, s33, v193
	v_add_u32_e32 v207, 0x110, v173
	v_lshl_add_u32 v198, v177, 2, s2
	ds_read_b32 v176, v176
	ds_read_b32 v178, v175 offset:128
	ds_read_b32 v177, v179
	ds_read_b32 v179, v180 offset:128
	ds_read_b32 v180, v181
	ds_read_b32 v196, v196 offset:128
	ds_read_b32 v181, v197
	ds_read_b32 v197, v198 offset:128
	v_add_u32_e32 v175, 0x107, v173
	v_lshl_add_u32 v204, v199, 2, s2
	v_add_u32_e32 v199, 0x10a, v173
	v_med3_i32 v208, v207, 0, v192
	v_med3_i32 v207, v207, s33, v193
	v_med3_i32 v198, v175, 0, v192
	v_med3_i32 v175, v175, s33, v193
	v_lshl_add_u32 v203, v200, 2, s2
	v_med3_i32 v200, v199, 0, v192
	v_lshl_add_u32 v210, v207, 2, s2
	v_add_u32_e32 v207, 0x111, v173
	v_lshl_add_u32 v198, v198, 2, s2
	v_lshl_add_u32 v175, v175, 2, s2
	v_med3_i32 v199, v199, s33, v193
	v_lshl_add_u32 v205, v200, 2, s2
	v_lshl_add_u32 v209, v208, 2, s2
	v_med3_i32 v208, v207, 0, v192
	v_med3_i32 v207, v207, s33, v193
	v_add_u32_e32 v215, 0x118, v173
	v_lshl_add_u32 v206, v199, 2, s2
	ds_read_b32 v198, v198
	ds_read_b32 v200, v175 offset:128
	ds_read_b32 v199, v201
	ds_read_b32 v201, v202 offset:128
	ds_read_b32 v202, v203
	ds_read_b32 v204, v204 offset:128
	ds_read_b32 v203, v205
	ds_read_b32 v205, v206 offset:128
	v_add_u32_e32 v175, 0x10f, v173
	v_lshl_add_u32 v212, v207, 2, s2
	v_add_u32_e32 v207, 0x112, v173
	v_med3_i32 v216, v215, 0, v192
	v_med3_i32 v215, v215, s33, v193
	v_med3_i32 v206, v175, 0, v192
	v_med3_i32 v175, v175, s33, v193
	v_lshl_add_u32 v211, v208, 2, s2
	v_med3_i32 v208, v207, 0, v192
	v_lshl_add_u32 v222, v215, 2, s2
	v_add_u32_e32 v215, 0x119, v173
	v_lshl_add_u32 v206, v206, 2, s2
	v_lshl_add_u32 v175, v175, 2, s2
	v_med3_i32 v207, v207, s33, v193
	v_lshl_add_u32 v213, v208, 2, s2
	v_lshl_add_u32 v217, v216, 2, s2
	v_med3_i32 v216, v215, 0, v192
	v_med3_i32 v215, v215, s33, v193
	v_lshl_add_u32 v214, v207, 2, s2
	ds_read_b32 v206, v206
	ds_read_b32 v208, v175 offset:128
	ds_read_b32 v207, v209
	ds_read_b32 v209, v210 offset:128
	ds_read_b32 v210, v211
	ds_read_b32 v212, v212 offset:128
	ds_read_b32 v211, v213
	ds_read_b32 v213, v214 offset:128
	v_add_u32_e32 v175, 0x117, v173
	v_lshl_add_u32 v220, v215, 2, s2
	v_add_u32_e32 v215, 0x11a, v173
	v_med3_i32 v214, v175, 0, v192
	v_lshl_add_u32 v218, v216, 2, s2
	v_med3_i32 v216, v215, 0, v192
	v_med3_i32 v215, v215, s33, v193
	v_med3_i32 v175, v175, s33, v193
	v_lshl_add_u32 v214, v214, 2, s2
	v_lshl_add_u32 v219, v216, 2, s2
	v_lshl_add_u32 v221, v215, 2, s2
	v_lshl_add_u32 v175, v175, 2, s2
	ds_read_b32 v214, v214
	ds_read_b32 v216, v175 offset:128
	ds_read_b32 v218, v218
	ds_read_b32 v219, v219
	ds_read_b32 v215, v217
	ds_read_b32 v221, v221 offset:128
	ds_read_b32 v220, v220 offset:128
	ds_read_b32 v217, v222 offset:128
	s_waitcnt lgkmcnt(4)
	v_pk_add_f32 v[94:95], v[94:95], v[218:219]
	s_waitcnt lgkmcnt(3)
	v_pk_add_f32 v[92:93], v[92:93], v[214:215]
	v_pk_add_f32 v[90:91], v[90:91], v[210:211]
	v_pk_add_f32 v[88:89], v[88:89], v[206:207]
	v_pk_add_f32 v[86:87], v[86:87], v[202:203]
	v_pk_add_f32 v[84:85], v[84:85], v[198:199]
	v_pk_add_f32 v[82:83], v[82:83], v[180:181]
	v_pk_add_f32 v[80:81], v[80:81], v[176:177]
	s_waitcnt lgkmcnt(1)
	v_pk_add_f32 v[78:79], v[78:79], v[220:221]
	s_waitcnt lgkmcnt(0)
	v_pk_add_f32 v[76:77], v[76:77], v[216:217]
	v_pk_add_f32 v[74:75], v[74:75], v[212:213]
	v_pk_add_f32 v[72:73], v[72:73], v[208:209]
	v_pk_add_f32 v[70:71], v[70:71], v[204:205]
	v_pk_add_f32 v[68:69], v[68:69], v[200:201]
	v_pk_add_f32 v[66:67], v[66:67], v[196:197]
	v_pk_add_f32 v[64:65], v[64:65], v[178:179]

; DI bool softmax_tile(f32x16& s0, f32x16& s1, float& m, float& l, float& alpha, bf16x8* pf, int lane, bool first, bool check) {
;     ...
;   pf[0] = pack8(s0, 0); pf[1] = pack8(s0, 8); pf[2] = pack8(s1, 0); pf[3] = pack8(s1, 8);
; DI void attn_diff_unit(const Params& p, int li, int b, int h, int qb, char* smem, bool pre, int nh, bool has_next) {
;     ...
;       const int kbase = kt * 128 + sub * 64;
;       const int relmin = kbase - (qb * 128 + 127), relmax = kbase + 63 - qb * 128;
;       const float cb = (relmin >= 128) ? cR : ((relmax <= -128) ? cL : 0.f);
;       f32x16 s0, s1;
; #pragma unroll
;       for (int i = 0; i < 16; ++i) { s0[i] = cb - m; s1[i] = cb - m; }
.Ldp_ck_done:
	v_cvt_pk_bf16_f32 v64, v64, v65
	v_cvt_pk_bf16_f32 v65, v66, v67
	v_cvt_pk_bf16_f32 v66, v68, v69
	v_cvt_pk_bf16_f32 v67, v70, v71
	v_cvt_pk_bf16_f32 v68, v72, v73
	v_cvt_pk_bf16_f32 v69, v74, v75
	v_cvt_pk_bf16_f32 v70, v76, v77
	v_cvt_pk_bf16_f32 v71, v78, v79
	v_cvt_pk_bf16_f32 v72, v80, v81
	v_cvt_pk_bf16_f32 v73, v82, v83
	v_cvt_pk_bf16_f32 v74, v84, v85
	v_cvt_pk_bf16_f32 v75, v86, v87
	v_cvt_pk_bf16_f32 v76, v88, v89
	v_cvt_pk_bf16_f32 v77, v90, v91
	v_cvt_pk_bf16_f32 v78, v92, v93
	v_cvt_pk_bf16_f32 v79, v94, v95
	s_add_i32 s2, s44, 64
	s_cmp_lg_u64 s[100:101], 0
	s_cbranch_scc1 .Ldp_i1_full
	s_cmp_eq_u32 s24, 0
	s_cbranch_scc1 .Ldp_i1_full
	s_cmp_ge_i32 s44, 0xff
	s_cbranch_scc1 .Ldp_i1_far
	s_cmp_le_i32 s2, 0xffffff41
	s_cbranch_scc0 .Ldp_i1_full
.Ldp_i1_far:
	s_mov_b64 s[2:3], -1
	s_branch .Ldp_i1_done
.Ldp_i1_full:
	s_cmp_ge_i32 s2, 0xff
	s_cselect_b64 vcc, -1, 0
	s_cmp_le_i32 s2, 0xffffff41
	s_cselect_b64 s[2:3], -1, 0
	v_cndmask_b32_e64 v196, 0, v156, s[2:3]
	v_cndmask_b32_e32 v196, v196, v157, vcc
	v_sub_f32_e32 v196, v196, v169
	v_mov_b32_e32 v197, v196
	v_mov_b64_e32 v[198:199], v[196:197]
	v_mov_b64_e32 v[200:201], v[196:197]
	v_mov_b64_e32 v[202:203], v[196:197]
	v_mov_b64_e32 v[204:205], v[196:197]
	v_mov_b64_e32 v[206:207], v[196:197]
	v_mov_b64_e32 v[208:209], v[196:197]
	v_mov_b64_e32 v[210:211], v[196:197]
; DI f32x16 mfma32(bf16x8 a, bf16x8 b, f32x16 c) { return __builtin_amdgcn_mfma_f32_32x32x16_bf16(a, b, c, 0, 0, 0); }
; DI void attn_diff_unit(const Params& p, int li, int b, int h, int qb, char* smem, bool pre, int nh, bool has_next) {
;     ...
;       {
;         bf16x8 kf[8];
; #pragma unroll
;         for (int s = 0; s < 4; ++s) {
;           kf[2 * s] = *(const bf16x8*)(ks + (sub * 64 + r32) * KR + (map * 64 + s * 16 + hh * 8) * 2);
;           kf[2 * s + 1] = *(const bf16x8*)(ks + (sub * 64 + 32 + r32) * KR + (map * 64 + s * 16 + hh * 8) * 2);
;         }
;         __builtin_amdgcn_sched_barrier(0); __builtin_amdgcn_s_setprio(1);
; #pragma unroll
;         for (int s = 0; s < 4; ++s) { s0 = mfma32(kf[2 * s], qf[s], s0); s1 = mfma32(kf[2 * s + 1], qf[s], s1); }
;       __builtin_amdgcn_s_setprio(0);
; }
;       if (relmin < 128 && relmax > -128) {
;         const int base = kbase - qpos + 255 + 4 * hh;
; #pragma unroll
;         for (int i = 0; i < 16; ++i) {
;           int i0 = base + (i & 3) + 8 * (i >> 2);
;           int i1 = i0 + 32;
;           i0 = i0 < 0 ? 0 : (i0 > 510 ? 510 : i0);
;           i1 = i1 < 0 ? 0 : (i1 > 510 ? 510 : i1);
;           s0[i] += tab[i0]; s1[i] += tab[i1];
;         }
;       }
.Ldp_i1_done:
	s_waitcnt lgkmcnt(0)
	s_nop 0
	v_mfma_f32_32x32x16_bf16 v[80:95], v[212:215], v[96:99], v[196:211]
	v_mfma_f32_32x32x16_bf16 v[196:211], v[216:219], v[96:99], v[196:211]
	v_mfma_f32_32x32x16_bf16 v[80:95], v[220:223], v[100:103], v[80:95]
	v_mfma_f32_32x32x16_bf16 v[196:211], v[224:227], v[100:103], v[196:211]
	v_mfma_f32_32x32x16_bf16 v[80:95], v[228:231], v[104:107], v[80:95]
	v_mfma_f32_32x32x16_bf16 v[196:211], v[232:235], v[104:107], v[196:211]
	v_mfma_f32_32x32x16_bf16 v[80:95], v[176:179], v[108:111], v[80:95]
	v_mfma_f32_32x32x16_bf16 v[196:211], v[242:245], v[108:111], v[196:211]
	s_or_b64 s[2:3], s[2:3], vcc
	s_and_b64 vcc, exec, s[2:3]
	s_cbranch_vccnz .Ldp_b1_skip
	s_add_i32 s2, 0, 0x25000
	v_add_u32_e32 v212, 0x13f, v173
	v_add_u32_e32 v228, 0x13f, v173
	v_add_u32_e32 v213, 0x140, v173
	v_add_u32_e32 v229, 0x140, v173
	v_add_u32_e32 v214, 0x141, v173
	v_add_u32_e32 v230, 0x141, v173
	v_add_u32_e32 v215, 0x142, v173
	v_add_u32_e32 v231, 0x142, v173
	v_add_u32_e32 v216, 0x147, v173
	v_add_u32_e32 v232, 0x147, v173
	v_add_u32_e32 v217, 0x148, v173
	v_add_u32_e32 v233, 0x148, v173
	v_add_u32_e32 v218, 0x149, v173
	v_add_u32_e32 v234, 0x149, v173
	v_add_u32_e32 v219, 0x14a, v173
	v_add_u32_e32 v235, 0x14a, v173
	v_add_u32_e32 v220, 0x14f, v173
	v_add_u32_e32 v176, 0x14f, v173
	v_add_u32_e32 v221, 0x150, v173
	v_add_u32_e32 v177, 0x150, v173
	v_add_u32_e32 v222, 0x151, v173
	v_add_u32_e32 v178, 0x151, v173
	v_add_u32_e32 v223, 0x152, v173
	v_add_u32_e32 v179, 0x152, v173
	v_add_u32_e32 v224, 0x157, v173
	v_add_u32_e32 v242, 0x157, v173
	v_add_u32_e32 v225, 0x158, v173
	v_add_u32_e32 v243, 0x158, v173
	v_add_u32_e32 v226, 0x159, v173
	v_add_u32_e32 v244, 0x159, v173
	v_add_u32_e32 v227, 0x15a, v173
	v_add_u32_e32 v245, 0x15a, v173
	v_med3_i32 v212, v212, 0, v192
	v_med3_i32 v228, v228, s33, v193
	v_med3_i32 v213, v213, 0, v192
	v_med3_i32 v229, v229, s33, v193
	v_med3_i32 v214, v214, 0, v192
	v_med3_i32 v230, v230, s33, v193
	v_med3_i32 v215, v215, 0, v192
	v_med3_i32 v231, v231, s33, v193
	v_med3_i32 v216, v216, 0, v192
	v_med3_i32 v232, v232, s33, v193
	v_med3_i32 v217, v217, 0, v192
	v_med3_i32 v233, v233, s33, v193
	v_med3_i32 v218, v218, 0, v192
	v_med3_i32 v234, v234, s33, v193
	v_med3_i32 v219, v219, 0, v192
	v_med3_i32 v235, v235, s33, v193
	v_med3_i32 v220, v220, 0, v192
	v_med3_i32 v176, v176, s33, v193
	v_med3_i32 v221, v221, 0, v192
	v_med3_i32 v177, v177, s33, v193
	v_med3_i32 v222, v222, 0, v192
	v_med3_i32 v178, v178, s33, v193
	v_med3_i32 v223, v223, 0, v192
	v_med3_i32 v179, v179, s33, v193
	v_med3_i32 v224, v224, 0, v192
	v_med3_i32 v242, v242, s33, v193
	v_med3_i32 v225, v225, 0, v192
	v_med3_i32 v243, v243, s33, v193
	v_med3_i32 v226, v226, 0, v192
	v_med3_i32 v244, v244, s33, v193
	v_med3_i32 v227, v227, 0, v192
	v_med3_i32 v245, v245, s33, v193
	v_lshl_add_u32 v212, v212, 2, s2
	v_lshl_add_u32 v228, v228, 2, s2
	v_lshl_add_u32 v213, v213, 2, s2
	v_lshl_add_u32 v229, v229, 2, s2
	v_lshl_add_u32 v214, v214, 2, s2
	v_lshl_add_u32 v230, v230, 2, s2
	v_lshl_add_u32 v215, v215, 2, s2
	v_lshl_add_u32 v231, v231, 2, s2
	v_lshl_add_u32 v216, v216, 2, s2
	v_lshl_add_u32 v232, v232, 2, s2
	v_lshl_add_u32 v217, v217, 2, s2
	v_lshl_add_u32 v233, v233, 2, s2
	v_lshl_add_u32 v218, v218, 2, s2
	v_lshl_add_u32 v234, v234, 2, s2
	v_lshl_add_u32 v219, v219, 2, s2
	v_lshl_add_u32 v235, v235, 2, s2
	v_lshl_add_u32 v220, v220, 2, s2
	v_lshl_add_u32 v176, v176, 2, s2
	v_lshl_add_u32 v221, v221, 2, s2
	v_lshl_add_u32 v177, v177, 2, s2
	v_lshl_add_u32 v222, v222, 2, s2
	v_lshl_add_u32 v178, v178, 2, s2
	v_lshl_add_u32 v223, v223, 2, s2
	v_lshl_add_u32 v179, v179, 2, s2
	v_lshl_add_u32 v224, v224, 2, s2
	v_lshl_add_u32 v242, v242, 2, s2
	v_lshl_add_u32 v225, v225, 2, s2
	v_lshl_add_u32 v243, v243, 2, s2
	v_lshl_add_u32 v226, v226, 2, s2
	v_lshl_add_u32 v244, v244, 2, s2
	v_lshl_add_u32 v227, v227, 2, s2
	v_lshl_add_u32 v245, v245, 2, s2
	ds_read_b32 v212, v212
	ds_read_b32 v228, v228 offset:128
	ds_read_b32 v213, v213
	ds_read_b32 v229, v229 offset:128
	ds_read_b32 v214, v214
	ds_read_b32 v230, v230 offset:128
	ds_read_b32 v215, v215
	ds_read_b32 v231, v231 offset:128
	ds_read_b32 v216, v216
	ds_read_b32 v232, v232 offset:128
	ds_read_b32 v217, v217
	ds_read_b32 v233, v233 offset:128
	ds_read_b32 v218, v218
	ds_read_b32 v234, v234 offset:128
	ds_read_b32 v219, v219
	ds_read_b32 v235, v235 offset:128
	ds_read_b32 v220, v220
	ds_read_b32 v176, v176 offset:128
	ds_read_b32 v221, v221
	ds_read_b32 v177, v177 offset:128
	ds_read_b32 v222, v222
	ds_read_b32 v178, v178 offset:128
	ds_read_b32 v223, v223
	ds_read_b32 v179, v179 offset:128
	ds_read_b32 v224, v224
	ds_read_b32 v242, v242 offset:128
	ds_read_b32 v225, v225
	ds_read_b32 v243, v243 offset:128
	ds_read_b32 v226, v226
	ds_read_b32 v244, v244 offset:128
	ds_read_b32 v227, v227
	ds_read_b32 v245, v245 offset:128
	s_waitcnt lgkmcnt(0)
	v_add_f32_e32 v80, v80, v212
	v_add_f32_e32 v196, v196, v228
	v_add_f32_e32 v81, v81, v213
	v_add_f32_e32 v197, v197, v229
	v_add_f32_e32 v82, v82, v214
	v_add_f32_e32 v198, v198, v230
	v_add_f32_e32 v83, v83, v215
	v_add_f32_e32 v199, v199, v231
	v_add_f32_e32 v84, v84, v216
	v_add_f32_e32 v200, v200, v232
	v_add_f32_e32 v85, v85, v217
	v_add_f32_e32 v201, v201, v233
	v_add_f32_e32 v86, v86, v218
	v_add_f32_e32 v202, v202, v234
	v_add_f32_e32 v87, v87, v219
	v_add_f32_e32 v203, v203, v235
	v_add_f32_e32 v88, v88, v220
	v_add_f32_e32 v204, v204, v176
	v_add_f32_e32 v89, v89, v221
	v_add_f32_e32 v205, v205, v177
	v_add_f32_e32 v90, v90, v222
	v_add_f32_e32 v206, v206, v178
	v_add_f32_e32 v91, v91, v223
	v_add_f32_e32 v207, v207, v179
	v_add_f32_e32 v92, v92, v224
	v_add_f32_e32 v208, v208, v242
	v_add_f32_e32 v93, v93, v225
	v_add_f32_e32 v209, v209, v243
	v_add_f32_e32 v94, v94, v226
	v_add_f32_e32 v210, v210, v244
	v_add_f32_e32 v95, v95, v227
	v_add_f32_e32 v211, v211, v245
